# P3 pool unit: 16 per-tile 8-byte MIX stores paired into 8 dwordx4 stores via v_permlane32_swap + v_permlane16_swap (lever 7.3 widen row-per-lane epilogue stores); vmcnt waits re-derived
# baseline (speedup 1.0000x reference)
.LBB0_557:
	v_mov_b64_e32 v[34:35], s[28:29]
	v_lshl_or_b32 v104, s8, 8, v140
	v_mad_i64_i32 v[34:35], s[10:11], v32, s18, v[34:35]
	v_ashrrev_i32_e32 v105, 31, v104
	v_lshl_add_u64 v[106:107], v[34:35], 0, s[4:5]
	v_lshlrev_b64 v[34:35], 1, v[104:105]
	v_or_b32_e32 v108, 16, v104
	v_lshl_add_u64 v[36:37], v[106:107], 0, v[34:35]
	v_ashrrev_i32_e32 v109, 31, v108
	v_or_b32_e32 v110, 32, v104
	v_or_b32_e32 v112, 48, v104
	s_waitcnt lgkmcnt(0)
	s_barrier
	v_mov_b32_e32 v170, v36
	v_mov_b32_e32 v171, v37
	v_lshlrev_b64 v[132:133], 12, v[32:33]
	v_lshl_add_u64 v[130:131], v[104:105], 2, s[60:61]
	v_lshl_add_u64 v[132:133], s[30:31], 0, v[132:133]
	v_mov_b32_e32 v64, v143
	v_add_u32_e32 v103, 0x10800, v143
	v_lshl_add_u64 v[132:133], v[104:105], 1, v[132:133]
	v_mbcnt_hi_u32_b32 v248, -1, v169
	v_lshrrev_b32_e32 v248, 4, v248
	v_lshlrev_b32_e32 v248, 3, v248
	v_mov_b32_e32 v249, 0
	v_lshl_add_u64 v[250:251], v[132:133], 0, v[248:249]
	ds_read_b128 v[174:177], v64
	ds_read_b128 v[178:181], v64 offset:64
	ds_read_b128 v[182:185], v64 offset:128
	ds_read_b128 v[186:189], v64 offset:192
	ds_read_b128 v[190:193], v64 offset:256
	ds_read_b128 v[194:197], v64 offset:320
	ds_read_b128 v[198:201], v64 offset:384
	ds_read_b128 v[202:205], v64 offset:448
	global_load_dwordx2 v[32:33], v[170:171], off
	global_load_dwordx2 v[34:35], v[170:171], off offset:32
	global_load_dwordx2 v[36:37], v[170:171], off offset:64
	global_load_dwordx2 v[38:39], v[170:171], off offset:96
	global_load_dwordx2 v[40:41], v[170:171], off offset:128
	global_load_dwordx2 v[42:43], v[170:171], off offset:160
	global_load_dwordx2 v[44:45], v[170:171], off offset:192
	global_load_dwordx2 v[46:47], v[170:171], off offset:224
	global_load_dwordx2 v[48:49], v[170:171], off offset:256
	global_load_dwordx2 v[50:51], v[170:171], off offset:288
	global_load_dwordx2 v[52:53], v[170:171], off offset:320
	global_load_dwordx2 v[54:55], v[170:171], off offset:352
	global_load_dwordx2 v[56:57], v[170:171], off offset:384
	global_load_dwordx2 v[58:59], v[170:171], off offset:416
	global_load_dwordx2 v[60:61], v[170:171], off offset:448
	global_load_dwordx2 v[62:63], v[170:171], off offset:480
	global_load_dwordx4 v[118:121], v[130:131], off
	global_load_dwordx4 v[122:125], v[130:131], off offset:64
	global_load_dwordx4 v[126:129], v[130:131], off offset:128
	s_waitcnt lgkmcnt(0)
	ds_read_b128 v[206:209], v64 offset:8448
	ds_read_b128 v[210:213], v64 offset:8512
	ds_read_b128 v[214:217], v64 offset:8576
	ds_read_b128 v[218:221], v64 offset:8640
	ds_read_b128 v[222:225], v64 offset:8704
	ds_read_b128 v[226:229], v64 offset:8768
	ds_read_b128 v[230:233], v64 offset:8832
	ds_read_b128 v[234:237], v64 offset:8896
	s_waitcnt vmcnt(26)
	v_mfma_f32_16x16x32_bf16 v[162:165], v[174:177], v[0:3], 0
	s_waitcnt vmcnt(25)
	v_mfma_f32_16x16x32_bf16 v[162:165], v[178:181], v[4:7], v[162:165]
	s_waitcnt vmcnt(24)
	v_mfma_f32_16x16x32_bf16 v[162:165], v[182:185], v[8:11], v[162:165]
	s_waitcnt vmcnt(23)
	v_mfma_f32_16x16x32_bf16 v[162:165], v[186:189], v[12:15], v[162:165]
	s_waitcnt vmcnt(22)
	v_mfma_f32_16x16x32_bf16 v[162:165], v[190:193], v[16:19], v[162:165]
	s_waitcnt vmcnt(21)
	v_mfma_f32_16x16x32_bf16 v[162:165], v[194:197], v[20:23], v[162:165]
	s_waitcnt vmcnt(20)
	v_mfma_f32_16x16x32_bf16 v[162:165], v[198:201], v[24:27], v[162:165]
	s_waitcnt vmcnt(19)
	v_mfma_f32_16x16x32_bf16 v[162:165], v[202:205], v[28:31], v[162:165]
	s_waitcnt vmcnt(18)
	v_lshlrev_b32_e32 v170, 16, v32
	v_and_b32_e32 v171, 0xffff0000, v32
	v_mul_f32_e32 v244, 0xbfb8aa3b, v170
	v_exp_f32_e32 v244, v244
	s_nop 0
	v_add_f32_e32 v244, 1.0, v244
	v_rcp_f32_e32 v172, v244
	v_mul_f32_e32 v244, 0xbfb8aa3b, v171
	v_exp_f32_e32 v244, v244
	s_nop 0
	v_add_f32_e32 v244, 1.0, v244
	v_rcp_f32_e32 v173, v244
	s_waitcnt vmcnt(2)
	v_pk_mul_f32 v[118:119], v[118:119], v[162:163]
	v_pk_mul_f32 v[120:121], v[120:121], v[164:165]
	v_pk_mul_f32 v[172:173], v[172:173], v[170:171]
	s_nop 0
	v_pk_mul_f32 v[118:119], v[172:173], v[118:119]
	s_nop 0
	v_cvt_pk_bf16_f32 v244, v118, v119
	v_lshlrev_b32_e32 v170, 16, v33
	v_and_b32_e32 v171, 0xffff0000, v33
	v_mul_f32_e32 v245, 0xbfb8aa3b, v170
	v_exp_f32_e32 v245, v245
	s_nop 0
	v_add_f32_e32 v245, 1.0, v245
	v_rcp_f32_e32 v172, v245
	v_mul_f32_e32 v245, 0xbfb8aa3b, v171
	v_exp_f32_e32 v245, v245
	s_nop 0
	v_add_f32_e32 v245, 1.0, v245
	v_rcp_f32_e32 v173, v245
	s_nop 1
	v_pk_mul_f32 v[172:173], v[172:173], v[170:171]
	s_nop 0
	v_pk_mul_f32 v[120:121], v[172:173], v[120:121]
	s_nop 0
	v_cvt_pk_bf16_f32 v245, v120, v121
	s_nop 0
	global_load_dwordx4 v[118:121], v[130:131], off offset:192
	s_waitcnt lgkmcnt(0)
	ds_read_b128 v[174:177], v64 offset:16896
	ds_read_b128 v[178:181], v64 offset:16960
	ds_read_b128 v[182:185], v64 offset:17024
	ds_read_b128 v[186:189], v64 offset:17088
	ds_read_b128 v[190:193], v64 offset:17152
	ds_read_b128 v[194:197], v64 offset:17216
	ds_read_b128 v[198:201], v64 offset:17280
	ds_read_b128 v[202:205], v64 offset:17344
	v_mfma_f32_16x16x32_bf16 v[162:165], v[206:209], v[0:3], 0
	v_mfma_f32_16x16x32_bf16 v[162:165], v[210:213], v[4:7], v[162:165]
	v_mfma_f32_16x16x32_bf16 v[162:165], v[214:217], v[8:11], v[162:165]
	v_mfma_f32_16x16x32_bf16 v[162:165], v[218:221], v[12:15], v[162:165]
	v_mfma_f32_16x16x32_bf16 v[162:165], v[222:225], v[16:19], v[162:165]
	v_mfma_f32_16x16x32_bf16 v[162:165], v[226:229], v[20:23], v[162:165]
	v_mfma_f32_16x16x32_bf16 v[162:165], v[230:233], v[24:27], v[162:165]
	v_mfma_f32_16x16x32_bf16 v[162:165], v[234:237], v[28:31], v[162:165]
	s_waitcnt vmcnt(18)
	v_lshlrev_b32_e32 v170, 16, v34
	v_and_b32_e32 v171, 0xffff0000, v34
	v_mul_f32_e32 v246, 0xbfb8aa3b, v170
	v_exp_f32_e32 v246, v246
	s_nop 0
	v_add_f32_e32 v246, 1.0, v246
	v_rcp_f32_e32 v172, v246
	v_mul_f32_e32 v246, 0xbfb8aa3b, v171
	v_exp_f32_e32 v246, v246
	s_nop 0
	v_add_f32_e32 v246, 1.0, v246
	v_rcp_f32_e32 v173, v246
	s_waitcnt vmcnt(2)
	v_pk_mul_f32 v[122:123], v[122:123], v[162:163]
	v_pk_mul_f32 v[124:125], v[124:125], v[164:165]
	v_pk_mul_f32 v[172:173], v[172:173], v[170:171]
	s_nop 0
	v_pk_mul_f32 v[122:123], v[172:173], v[122:123]
	s_nop 0
	v_cvt_pk_bf16_f32 v246, v122, v123
	v_lshlrev_b32_e32 v170, 16, v35
	v_and_b32_e32 v171, 0xffff0000, v35
	v_mul_f32_e32 v247, 0xbfb8aa3b, v170
	v_exp_f32_e32 v247, v247
	s_nop 0
	v_add_f32_e32 v247, 1.0, v247
	v_rcp_f32_e32 v172, v247
	v_mul_f32_e32 v247, 0xbfb8aa3b, v171
	v_exp_f32_e32 v247, v247
	s_nop 0
	v_add_f32_e32 v247, 1.0, v247
	v_rcp_f32_e32 v173, v247
	s_nop 1
	v_pk_mul_f32 v[172:173], v[172:173], v[170:171]
	s_nop 0
	v_pk_mul_f32 v[124:125], v[172:173], v[124:125]
	s_nop 0
	v_cvt_pk_bf16_f32 v247, v124, v125
	s_nop 0
	s_nop 1
	v_permlane32_swap_b32_e32 v244, v246
	v_permlane32_swap_b32_e32 v245, v247
	s_nop 0
	v_permlane16_swap_b32_e32 v244, v246
	v_permlane16_swap_b32_e32 v245, v247
	s_nop 0
	global_store_dwordx4 v[250:251], v[244:247], off offset:2048
	global_load_dwordx4 v[122:125], v[130:131], off offset:256
	s_waitcnt lgkmcnt(0)
	ds_read_b128 v[206:209], v64 offset:25344
	ds_read_b128 v[210:213], v64 offset:25408
	ds_read_b128 v[214:217], v64 offset:25472
	ds_read_b128 v[218:221], v64 offset:25536
	ds_read_b128 v[222:225], v64 offset:25600
	ds_read_b128 v[226:229], v64 offset:25664
	ds_read_b128 v[230:233], v64 offset:25728
	ds_read_b128 v[234:237], v64 offset:25792
	v_mfma_f32_16x16x32_bf16 v[162:165], v[174:177], v[0:3], 0
	v_mfma_f32_16x16x32_bf16 v[162:165], v[178:181], v[4:7], v[162:165]
	v_mfma_f32_16x16x32_bf16 v[162:165], v[182:185], v[8:11], v[162:165]
	v_mfma_f32_16x16x32_bf16 v[162:165], v[186:189], v[12:15], v[162:165]
	v_mfma_f32_16x16x32_bf16 v[162:165], v[190:193], v[16:19], v[162:165]
	v_mfma_f32_16x16x32_bf16 v[162:165], v[194:197], v[20:23], v[162:165]
	v_mfma_f32_16x16x32_bf16 v[162:165], v[198:201], v[24:27], v[162:165]
	v_mfma_f32_16x16x32_bf16 v[162:165], v[202:205], v[28:31], v[162:165]
	s_waitcnt vmcnt(19)
	v_lshlrev_b32_e32 v170, 16, v36
	v_and_b32_e32 v171, 0xffff0000, v36
	v_mul_f32_e32 v244, 0xbfb8aa3b, v170
	v_exp_f32_e32 v244, v244
	s_nop 0
	v_add_f32_e32 v244, 1.0, v244
	v_rcp_f32_e32 v172, v244
	v_mul_f32_e32 v244, 0xbfb8aa3b, v171
	v_exp_f32_e32 v244, v244
	s_nop 0
	v_add_f32_e32 v244, 1.0, v244
	v_rcp_f32_e32 v173, v244
	s_waitcnt vmcnt(3)
	v_pk_mul_f32 v[126:127], v[126:127], v[162:163]
	v_pk_mul_f32 v[128:129], v[128:129], v[164:165]
	v_pk_mul_f32 v[172:173], v[172:173], v[170:171]
	s_nop 0
	v_pk_mul_f32 v[126:127], v[172:173], v[126:127]
	s_nop 0
	v_cvt_pk_bf16_f32 v244, v126, v127
	v_lshlrev_b32_e32 v170, 16, v37
	v_and_b32_e32 v171, 0xffff0000, v37
	v_mul_f32_e32 v245, 0xbfb8aa3b, v170
	v_exp_f32_e32 v245, v245
	s_nop 0
	v_add_f32_e32 v245, 1.0, v245
	v_rcp_f32_e32 v172, v245
	v_mul_f32_e32 v245, 0xbfb8aa3b, v171
	v_exp_f32_e32 v245, v245
	s_nop 0
	v_add_f32_e32 v245, 1.0, v245
	v_rcp_f32_e32 v173, v245
	s_nop 1
	v_pk_mul_f32 v[172:173], v[172:173], v[170:171]
	s_nop 0
	v_pk_mul_f32 v[128:129], v[172:173], v[128:129]
	s_nop 0
	v_cvt_pk_bf16_f32 v245, v128, v129
	s_nop 0
	global_load_dwordx4 v[126:129], v[130:131], off offset:320
	s_waitcnt lgkmcnt(0)
	ds_read_b128 v[174:177], v64 offset:33792
	ds_read_b128 v[178:181], v64 offset:33856
	ds_read_b128 v[182:185], v64 offset:33920
	ds_read_b128 v[186:189], v64 offset:33984
	ds_read_b128 v[190:193], v64 offset:34048
	ds_read_b128 v[194:197], v64 offset:34112
	ds_read_b128 v[198:201], v64 offset:34176
	ds_read_b128 v[202:205], v64 offset:34240
	v_mfma_f32_16x16x32_bf16 v[162:165], v[206:209], v[0:3], 0
	v_mfma_f32_16x16x32_bf16 v[162:165], v[210:213], v[4:7], v[162:165]
	v_mfma_f32_16x16x32_bf16 v[162:165], v[214:217], v[8:11], v[162:165]
	v_mfma_f32_16x16x32_bf16 v[162:165], v[218:221], v[12:15], v[162:165]
	v_mfma_f32_16x16x32_bf16 v[162:165], v[222:225], v[16:19], v[162:165]
	v_mfma_f32_16x16x32_bf16 v[162:165], v[226:229], v[20:23], v[162:165]
	v_mfma_f32_16x16x32_bf16 v[162:165], v[230:233], v[24:27], v[162:165]
	v_mfma_f32_16x16x32_bf16 v[162:165], v[234:237], v[28:31], v[162:165]
	s_waitcnt vmcnt(19)
	v_lshlrev_b32_e32 v170, 16, v38
	v_and_b32_e32 v171, 0xffff0000, v38
	v_mul_f32_e32 v246, 0xbfb8aa3b, v170
	v_exp_f32_e32 v246, v246
	s_nop 0
	v_add_f32_e32 v246, 1.0, v246
	v_rcp_f32_e32 v172, v246
	v_mul_f32_e32 v246, 0xbfb8aa3b, v171
	v_exp_f32_e32 v246, v246
	s_nop 0
	v_add_f32_e32 v246, 1.0, v246
	v_rcp_f32_e32 v173, v246
	s_waitcnt vmcnt(3)
	v_pk_mul_f32 v[118:119], v[118:119], v[162:163]
	v_pk_mul_f32 v[120:121], v[120:121], v[164:165]
	v_pk_mul_f32 v[172:173], v[172:173], v[170:171]
	s_nop 0
	v_pk_mul_f32 v[118:119], v[172:173], v[118:119]
	s_nop 0
	v_cvt_pk_bf16_f32 v246, v118, v119
	v_lshlrev_b32_e32 v170, 16, v39
	v_and_b32_e32 v171, 0xffff0000, v39
	v_mul_f32_e32 v247, 0xbfb8aa3b, v170
	v_exp_f32_e32 v247, v247
	s_nop 0
	v_add_f32_e32 v247, 1.0, v247
	v_rcp_f32_e32 v172, v247
	v_mul_f32_e32 v247, 0xbfb8aa3b, v171
	v_exp_f32_e32 v247, v247
	s_nop 0
	v_add_f32_e32 v247, 1.0, v247
	v_rcp_f32_e32 v173, v247
	s_nop 1
	v_pk_mul_f32 v[172:173], v[172:173], v[170:171]
	s_nop 0
	v_pk_mul_f32 v[120:121], v[172:173], v[120:121]
	s_nop 0
	v_cvt_pk_bf16_f32 v247, v120, v121
	s_nop 0
	s_nop 1
	v_permlane32_swap_b32_e32 v244, v246
	v_permlane32_swap_b32_e32 v245, v247
	s_nop 0
	v_permlane16_swap_b32_e32 v244, v246
	v_permlane16_swap_b32_e32 v245, v247
	s_nop 0
	global_store_dwordx4 v[250:251], v[244:247], off offset:2112
	global_load_dwordx4 v[118:121], v[130:131], off offset:384
	s_waitcnt lgkmcnt(0)
	ds_read_b128 v[206:209], v64 offset:42240
	ds_read_b128 v[210:213], v64 offset:42304
	ds_read_b128 v[214:217], v64 offset:42368
	ds_read_b128 v[218:221], v64 offset:42432
	ds_read_b128 v[222:225], v64 offset:42496
	ds_read_b128 v[226:229], v64 offset:42560
	ds_read_b128 v[230:233], v64 offset:42624
	ds_read_b128 v[234:237], v64 offset:42688
	v_mfma_f32_16x16x32_bf16 v[162:165], v[174:177], v[0:3], 0
	v_mfma_f32_16x16x32_bf16 v[162:165], v[178:181], v[4:7], v[162:165]
	v_mfma_f32_16x16x32_bf16 v[162:165], v[182:185], v[8:11], v[162:165]
	v_mfma_f32_16x16x32_bf16 v[162:165], v[186:189], v[12:15], v[162:165]
	v_mfma_f32_16x16x32_bf16 v[162:165], v[190:193], v[16:19], v[162:165]
	v_mfma_f32_16x16x32_bf16 v[162:165], v[194:197], v[20:23], v[162:165]
	v_mfma_f32_16x16x32_bf16 v[162:165], v[198:201], v[24:27], v[162:165]
	v_mfma_f32_16x16x32_bf16 v[162:165], v[202:205], v[28:31], v[162:165]
	s_waitcnt vmcnt(20)
	v_lshlrev_b32_e32 v170, 16, v40
	v_and_b32_e32 v171, 0xffff0000, v40
	v_mul_f32_e32 v244, 0xbfb8aa3b, v170
	v_exp_f32_e32 v244, v244
	s_nop 0
	v_add_f32_e32 v244, 1.0, v244
	v_rcp_f32_e32 v172, v244
	v_mul_f32_e32 v244, 0xbfb8aa3b, v171
	v_exp_f32_e32 v244, v244
	s_nop 0
	v_add_f32_e32 v244, 1.0, v244
	v_rcp_f32_e32 v173, v244
	s_waitcnt vmcnt(3)
	v_pk_mul_f32 v[122:123], v[122:123], v[162:163]
	v_pk_mul_f32 v[124:125], v[124:125], v[164:165]
	v_pk_mul_f32 v[172:173], v[172:173], v[170:171]
	s_nop 0
	v_pk_mul_f32 v[122:123], v[172:173], v[122:123]
	s_nop 0
	v_cvt_pk_bf16_f32 v244, v122, v123
	v_lshlrev_b32_e32 v170, 16, v41
	v_and_b32_e32 v171, 0xffff0000, v41
	v_mul_f32_e32 v245, 0xbfb8aa3b, v170
	v_exp_f32_e32 v245, v245
	s_nop 0
	v_add_f32_e32 v245, 1.0, v245
	v_rcp_f32_e32 v172, v245
	v_mul_f32_e32 v245, 0xbfb8aa3b, v171
	v_exp_f32_e32 v245, v245
	s_nop 0
	v_add_f32_e32 v245, 1.0, v245
	v_rcp_f32_e32 v173, v245
	s_nop 1
	v_pk_mul_f32 v[172:173], v[172:173], v[170:171]
	s_nop 0
	v_pk_mul_f32 v[124:125], v[172:173], v[124:125]
	s_nop 0
	v_cvt_pk_bf16_f32 v245, v124, v125
	s_nop 0
	global_load_dwordx4 v[122:125], v[130:131], off offset:448
	s_waitcnt lgkmcnt(0)
	ds_read_b128 v[174:177], v64 offset:50688
	ds_read_b128 v[178:181], v64 offset:50752
	ds_read_b128 v[182:185], v64 offset:50816
	ds_read_b128 v[186:189], v64 offset:50880
	ds_read_b128 v[190:193], v64 offset:50944
	ds_read_b128 v[194:197], v64 offset:51008
	ds_read_b128 v[198:201], v64 offset:51072
	ds_read_b128 v[202:205], v64 offset:51136
	v_mfma_f32_16x16x32_bf16 v[162:165], v[206:209], v[0:3], 0
	v_mfma_f32_16x16x32_bf16 v[162:165], v[210:213], v[4:7], v[162:165]
	v_mfma_f32_16x16x32_bf16 v[162:165], v[214:217], v[8:11], v[162:165]
	v_mfma_f32_16x16x32_bf16 v[162:165], v[218:221], v[12:15], v[162:165]
	v_mfma_f32_16x16x32_bf16 v[162:165], v[222:225], v[16:19], v[162:165]
	v_mfma_f32_16x16x32_bf16 v[162:165], v[226:229], v[20:23], v[162:165]
	v_mfma_f32_16x16x32_bf16 v[162:165], v[230:233], v[24:27], v[162:165]
	v_mfma_f32_16x16x32_bf16 v[162:165], v[234:237], v[28:31], v[162:165]
	s_waitcnt vmcnt(20)
	v_lshlrev_b32_e32 v170, 16, v42
	v_and_b32_e32 v171, 0xffff0000, v42
	v_mul_f32_e32 v246, 0xbfb8aa3b, v170
	v_exp_f32_e32 v246, v246
	s_nop 0
	v_add_f32_e32 v246, 1.0, v246
	v_rcp_f32_e32 v172, v246
	v_mul_f32_e32 v246, 0xbfb8aa3b, v171
	v_exp_f32_e32 v246, v246
	s_nop 0
	v_add_f32_e32 v246, 1.0, v246
	v_rcp_f32_e32 v173, v246
	s_waitcnt vmcnt(3)
	v_pk_mul_f32 v[126:127], v[126:127], v[162:163]
	v_pk_mul_f32 v[128:129], v[128:129], v[164:165]
	v_pk_mul_f32 v[172:173], v[172:173], v[170:171]
	s_nop 0
	v_pk_mul_f32 v[126:127], v[172:173], v[126:127]
	s_nop 0
	v_cvt_pk_bf16_f32 v246, v126, v127
	v_lshlrev_b32_e32 v170, 16, v43
	v_and_b32_e32 v171, 0xffff0000, v43
	v_mul_f32_e32 v247, 0xbfb8aa3b, v170
	v_exp_f32_e32 v247, v247
	s_nop 0
	v_add_f32_e32 v247, 1.0, v247
	v_rcp_f32_e32 v172, v247
	v_mul_f32_e32 v247, 0xbfb8aa3b, v171
	v_exp_f32_e32 v247, v247
	s_nop 0
	v_add_f32_e32 v247, 1.0, v247
	v_rcp_f32_e32 v173, v247
	s_nop 1
	v_pk_mul_f32 v[172:173], v[172:173], v[170:171]
	s_nop 0
	v_pk_mul_f32 v[128:129], v[172:173], v[128:129]
	s_nop 0
	v_cvt_pk_bf16_f32 v247, v128, v129
	s_nop 0
	s_nop 1
	v_permlane32_swap_b32_e32 v244, v246
	v_permlane32_swap_b32_e32 v245, v247
	s_nop 0
	v_permlane16_swap_b32_e32 v244, v246
	v_permlane16_swap_b32_e32 v245, v247
	s_nop 0
	global_store_dwordx4 v[250:251], v[244:247], off offset:2176
	global_load_dwordx4 v[126:129], v[130:131], off offset:512
	s_waitcnt lgkmcnt(0)
	ds_read_b128 v[206:209], v64 offset:59136
	ds_read_b128 v[210:213], v64 offset:59200
	ds_read_b128 v[214:217], v64 offset:59264
	ds_read_b128 v[218:221], v64 offset:59328
	ds_read_b128 v[222:225], v64 offset:59392
	ds_read_b128 v[226:229], v64 offset:59456
	ds_read_b128 v[230:233], v64 offset:59520
	ds_read_b128 v[234:237], v64 offset:59584
	v_mfma_f32_16x16x32_bf16 v[162:165], v[174:177], v[0:3], 0
	v_mfma_f32_16x16x32_bf16 v[162:165], v[178:181], v[4:7], v[162:165]
	v_mfma_f32_16x16x32_bf16 v[162:165], v[182:185], v[8:11], v[162:165]
	v_mfma_f32_16x16x32_bf16 v[162:165], v[186:189], v[12:15], v[162:165]
	v_mfma_f32_16x16x32_bf16 v[162:165], v[190:193], v[16:19], v[162:165]
	v_mfma_f32_16x16x32_bf16 v[162:165], v[194:197], v[20:23], v[162:165]
	v_mfma_f32_16x16x32_bf16 v[162:165], v[198:201], v[24:27], v[162:165]
	v_mfma_f32_16x16x32_bf16 v[162:165], v[202:205], v[28:31], v[162:165]
	s_waitcnt vmcnt(21)
	v_lshlrev_b32_e32 v170, 16, v44
	v_and_b32_e32 v171, 0xffff0000, v44
	v_mul_f32_e32 v244, 0xbfb8aa3b, v170
	v_exp_f32_e32 v244, v244
	s_nop 0
	v_add_f32_e32 v244, 1.0, v244
	v_rcp_f32_e32 v172, v244
	v_mul_f32_e32 v244, 0xbfb8aa3b, v171
	v_exp_f32_e32 v244, v244
	s_nop 0
	v_add_f32_e32 v244, 1.0, v244
	v_rcp_f32_e32 v173, v244
	s_waitcnt vmcnt(3)
	v_pk_mul_f32 v[118:119], v[118:119], v[162:163]
	v_pk_mul_f32 v[120:121], v[120:121], v[164:165]
	v_pk_mul_f32 v[172:173], v[172:173], v[170:171]
	s_nop 0
	v_pk_mul_f32 v[118:119], v[172:173], v[118:119]
	s_nop 0
	v_cvt_pk_bf16_f32 v244, v118, v119
	v_lshlrev_b32_e32 v170, 16, v45
	v_and_b32_e32 v171, 0xffff0000, v45
	v_mul_f32_e32 v245, 0xbfb8aa3b, v170
	v_exp_f32_e32 v245, v245
	s_nop 0
	v_add_f32_e32 v245, 1.0, v245
	v_rcp_f32_e32 v172, v245
	v_mul_f32_e32 v245, 0xbfb8aa3b, v171
	v_exp_f32_e32 v245, v245
	s_nop 0
	v_add_f32_e32 v245, 1.0, v245
	v_rcp_f32_e32 v173, v245
	s_nop 1
	v_pk_mul_f32 v[172:173], v[172:173], v[170:171]
	s_nop 0
	v_pk_mul_f32 v[120:121], v[172:173], v[120:121]
	s_nop 0
	v_cvt_pk_bf16_f32 v245, v120, v121
	s_nop 0
	global_load_dwordx4 v[118:121], v[130:131], off offset:576
	s_waitcnt lgkmcnt(0)
	ds_read_b128 v[174:177], v103
	ds_read_b128 v[178:181], v103 offset:64
	ds_read_b128 v[182:185], v103 offset:128
	ds_read_b128 v[186:189], v103 offset:192
	ds_read_b128 v[190:193], v103 offset:256
	ds_read_b128 v[194:197], v103 offset:320
	ds_read_b128 v[198:201], v103 offset:384
	ds_read_b128 v[202:205], v103 offset:448
	v_mfma_f32_16x16x32_bf16 v[162:165], v[206:209], v[0:3], 0
	v_mfma_f32_16x16x32_bf16 v[162:165], v[210:213], v[4:7], v[162:165]
	v_mfma_f32_16x16x32_bf16 v[162:165], v[214:217], v[8:11], v[162:165]
	v_mfma_f32_16x16x32_bf16 v[162:165], v[218:221], v[12:15], v[162:165]
	v_mfma_f32_16x16x32_bf16 v[162:165], v[222:225], v[16:19], v[162:165]
	v_mfma_f32_16x16x32_bf16 v[162:165], v[226:229], v[20:23], v[162:165]
	v_mfma_f32_16x16x32_bf16 v[162:165], v[230:233], v[24:27], v[162:165]
	v_mfma_f32_16x16x32_bf16 v[162:165], v[234:237], v[28:31], v[162:165]
	s_waitcnt vmcnt(21)
	v_lshlrev_b32_e32 v170, 16, v46
	v_and_b32_e32 v171, 0xffff0000, v46
	v_mul_f32_e32 v246, 0xbfb8aa3b, v170
	v_exp_f32_e32 v246, v246
	s_nop 0
	v_add_f32_e32 v246, 1.0, v246
	v_rcp_f32_e32 v172, v246
	v_mul_f32_e32 v246, 0xbfb8aa3b, v171
	v_exp_f32_e32 v246, v246
	s_nop 0
	v_add_f32_e32 v246, 1.0, v246
	v_rcp_f32_e32 v173, v246
	s_waitcnt vmcnt(3)
	v_pk_mul_f32 v[122:123], v[122:123], v[162:163]
	v_pk_mul_f32 v[124:125], v[124:125], v[164:165]
	v_pk_mul_f32 v[172:173], v[172:173], v[170:171]
	s_nop 0
	v_pk_mul_f32 v[122:123], v[172:173], v[122:123]
	s_nop 0
	v_cvt_pk_bf16_f32 v246, v122, v123
	v_lshlrev_b32_e32 v170, 16, v47
	v_and_b32_e32 v171, 0xffff0000, v47
	v_mul_f32_e32 v247, 0xbfb8aa3b, v170
	v_exp_f32_e32 v247, v247
	s_nop 0
	v_add_f32_e32 v247, 1.0, v247
	v_rcp_f32_e32 v172, v247
	v_mul_f32_e32 v247, 0xbfb8aa3b, v171
	v_exp_f32_e32 v247, v247
	s_nop 0
	v_add_f32_e32 v247, 1.0, v247
	v_rcp_f32_e32 v173, v247
	s_nop 1
	v_pk_mul_f32 v[172:173], v[172:173], v[170:171]
	s_nop 0
	v_pk_mul_f32 v[124:125], v[172:173], v[124:125]
	s_nop 0
	v_cvt_pk_bf16_f32 v247, v124, v125
	s_nop 0
	s_nop 1
	v_permlane32_swap_b32_e32 v244, v246
	v_permlane32_swap_b32_e32 v245, v247
	s_nop 0
	v_permlane16_swap_b32_e32 v244, v246
	v_permlane16_swap_b32_e32 v245, v247
	s_nop 0
	global_store_dwordx4 v[250:251], v[244:247], off offset:2240
	global_load_dwordx4 v[122:125], v[130:131], off offset:640
	s_waitcnt lgkmcnt(0)
	ds_read_b128 v[206:209], v103 offset:8448
	ds_read_b128 v[210:213], v103 offset:8512
	ds_read_b128 v[214:217], v103 offset:8576
	ds_read_b128 v[218:221], v103 offset:8640
	ds_read_b128 v[222:225], v103 offset:8704
	ds_read_b128 v[226:229], v103 offset:8768
	ds_read_b128 v[230:233], v103 offset:8832
	ds_read_b128 v[234:237], v103 offset:8896
	v_mfma_f32_16x16x32_bf16 v[162:165], v[174:177], v[0:3], 0
	v_mfma_f32_16x16x32_bf16 v[162:165], v[178:181], v[4:7], v[162:165]
	v_mfma_f32_16x16x32_bf16 v[162:165], v[182:185], v[8:11], v[162:165]
	v_mfma_f32_16x16x32_bf16 v[162:165], v[186:189], v[12:15], v[162:165]
	v_mfma_f32_16x16x32_bf16 v[162:165], v[190:193], v[16:19], v[162:165]
	v_mfma_f32_16x16x32_bf16 v[162:165], v[194:197], v[20:23], v[162:165]
	v_mfma_f32_16x16x32_bf16 v[162:165], v[198:201], v[24:27], v[162:165]
	v_mfma_f32_16x16x32_bf16 v[162:165], v[202:205], v[28:31], v[162:165]
	s_waitcnt vmcnt(22)
	v_lshlrev_b32_e32 v170, 16, v48
	v_and_b32_e32 v171, 0xffff0000, v48
	v_mul_f32_e32 v244, 0xbfb8aa3b, v170
	v_exp_f32_e32 v244, v244
	s_nop 0
	v_add_f32_e32 v244, 1.0, v244
	v_rcp_f32_e32 v172, v244
	v_mul_f32_e32 v244, 0xbfb8aa3b, v171
	v_exp_f32_e32 v244, v244
	s_nop 0
	v_add_f32_e32 v244, 1.0, v244
	v_rcp_f32_e32 v173, v244
	s_waitcnt vmcnt(3)
	v_pk_mul_f32 v[126:127], v[126:127], v[162:163]
	v_pk_mul_f32 v[128:129], v[128:129], v[164:165]
	v_pk_mul_f32 v[172:173], v[172:173], v[170:171]
	s_nop 0
	v_pk_mul_f32 v[126:127], v[172:173], v[126:127]
	s_nop 0
	v_cvt_pk_bf16_f32 v244, v126, v127
	v_lshlrev_b32_e32 v170, 16, v49
	v_and_b32_e32 v171, 0xffff0000, v49
	v_mul_f32_e32 v245, 0xbfb8aa3b, v170
	v_exp_f32_e32 v245, v245
	s_nop 0
	v_add_f32_e32 v245, 1.0, v245
	v_rcp_f32_e32 v172, v245
	v_mul_f32_e32 v245, 0xbfb8aa3b, v171
	v_exp_f32_e32 v245, v245
	s_nop 0
	v_add_f32_e32 v245, 1.0, v245
	v_rcp_f32_e32 v173, v245
	s_nop 1
	v_pk_mul_f32 v[172:173], v[172:173], v[170:171]
	s_nop 0
	v_pk_mul_f32 v[128:129], v[172:173], v[128:129]
	s_nop 0
	v_cvt_pk_bf16_f32 v245, v128, v129
	s_nop 0
	global_load_dwordx4 v[126:129], v[130:131], off offset:704
	s_waitcnt lgkmcnt(0)
	ds_read_b128 v[174:177], v103 offset:16896
	ds_read_b128 v[178:181], v103 offset:16960
	ds_read_b128 v[182:185], v103 offset:17024
	ds_read_b128 v[186:189], v103 offset:17088
	ds_read_b128 v[190:193], v103 offset:17152
	ds_read_b128 v[194:197], v103 offset:17216
	ds_read_b128 v[198:201], v103 offset:17280
	ds_read_b128 v[202:205], v103 offset:17344
	v_mfma_f32_16x16x32_bf16 v[162:165], v[206:209], v[0:3], 0
	v_mfma_f32_16x16x32_bf16 v[162:165], v[210:213], v[4:7], v[162:165]
	v_mfma_f32_16x16x32_bf16 v[162:165], v[214:217], v[8:11], v[162:165]
	v_mfma_f32_16x16x32_bf16 v[162:165], v[218:221], v[12:15], v[162:165]
	v_mfma_f32_16x16x32_bf16 v[162:165], v[222:225], v[16:19], v[162:165]
	v_mfma_f32_16x16x32_bf16 v[162:165], v[226:229], v[20:23], v[162:165]
	v_mfma_f32_16x16x32_bf16 v[162:165], v[230:233], v[24:27], v[162:165]
	v_mfma_f32_16x16x32_bf16 v[162:165], v[234:237], v[28:31], v[162:165]
	s_waitcnt vmcnt(22)
	v_lshlrev_b32_e32 v170, 16, v50
	v_and_b32_e32 v171, 0xffff0000, v50
	v_mul_f32_e32 v246, 0xbfb8aa3b, v170
	v_exp_f32_e32 v246, v246
	s_nop 0
	v_add_f32_e32 v246, 1.0, v246
	v_rcp_f32_e32 v172, v246
	v_mul_f32_e32 v246, 0xbfb8aa3b, v171
	v_exp_f32_e32 v246, v246
	s_nop 0
	v_add_f32_e32 v246, 1.0, v246
	v_rcp_f32_e32 v173, v246
	s_waitcnt vmcnt(3)
	v_pk_mul_f32 v[118:119], v[118:119], v[162:163]
	v_pk_mul_f32 v[120:121], v[120:121], v[164:165]
	v_pk_mul_f32 v[172:173], v[172:173], v[170:171]
	s_nop 0
	v_pk_mul_f32 v[118:119], v[172:173], v[118:119]
	s_nop 0
	v_cvt_pk_bf16_f32 v246, v118, v119
	v_lshlrev_b32_e32 v170, 16, v51
	v_and_b32_e32 v171, 0xffff0000, v51
	v_mul_f32_e32 v247, 0xbfb8aa3b, v170
	v_exp_f32_e32 v247, v247
	s_nop 0
	v_add_f32_e32 v247, 1.0, v247
	v_rcp_f32_e32 v172, v247
	v_mul_f32_e32 v247, 0xbfb8aa3b, v171
	v_exp_f32_e32 v247, v247
	s_nop 0
	v_add_f32_e32 v247, 1.0, v247
	v_rcp_f32_e32 v173, v247
	s_nop 1
	v_pk_mul_f32 v[172:173], v[172:173], v[170:171]
	s_nop 0
	v_pk_mul_f32 v[120:121], v[172:173], v[120:121]
	s_nop 0
	v_cvt_pk_bf16_f32 v247, v120, v121
	s_nop 0
	s_nop 1
	v_permlane32_swap_b32_e32 v244, v246
	v_permlane32_swap_b32_e32 v245, v247
	s_nop 0
	v_permlane16_swap_b32_e32 v244, v246
	v_permlane16_swap_b32_e32 v245, v247
	s_nop 0
	global_store_dwordx4 v[250:251], v[244:247], off offset:2304
	global_load_dwordx4 v[118:121], v[130:131], off offset:768
	s_waitcnt lgkmcnt(0)
	ds_read_b128 v[206:209], v103 offset:25344
	ds_read_b128 v[210:213], v103 offset:25408
	ds_read_b128 v[214:217], v103 offset:25472
	ds_read_b128 v[218:221], v103 offset:25536
	ds_read_b128 v[222:225], v103 offset:25600
	ds_read_b128 v[226:229], v103 offset:25664
	ds_read_b128 v[230:233], v103 offset:25728
	ds_read_b128 v[234:237], v103 offset:25792
	v_mfma_f32_16x16x32_bf16 v[162:165], v[174:177], v[0:3], 0
	v_mfma_f32_16x16x32_bf16 v[162:165], v[178:181], v[4:7], v[162:165]
	v_mfma_f32_16x16x32_bf16 v[162:165], v[182:185], v[8:11], v[162:165]
	v_mfma_f32_16x16x32_bf16 v[162:165], v[186:189], v[12:15], v[162:165]
	v_mfma_f32_16x16x32_bf16 v[162:165], v[190:193], v[16:19], v[162:165]
	v_mfma_f32_16x16x32_bf16 v[162:165], v[194:197], v[20:23], v[162:165]
	v_mfma_f32_16x16x32_bf16 v[162:165], v[198:201], v[24:27], v[162:165]
	v_mfma_f32_16x16x32_bf16 v[162:165], v[202:205], v[28:31], v[162:165]
	s_waitcnt vmcnt(23)
	v_lshlrev_b32_e32 v170, 16, v52
	v_and_b32_e32 v171, 0xffff0000, v52
	v_mul_f32_e32 v244, 0xbfb8aa3b, v170
	v_exp_f32_e32 v244, v244
	s_nop 0
	v_add_f32_e32 v244, 1.0, v244
	v_rcp_f32_e32 v172, v244
	v_mul_f32_e32 v244, 0xbfb8aa3b, v171
	v_exp_f32_e32 v244, v244
	s_nop 0
	v_add_f32_e32 v244, 1.0, v244
	v_rcp_f32_e32 v173, v244
	s_waitcnt vmcnt(3)
	v_pk_mul_f32 v[122:123], v[122:123], v[162:163]
	v_pk_mul_f32 v[124:125], v[124:125], v[164:165]
	v_pk_mul_f32 v[172:173], v[172:173], v[170:171]
	s_nop 0
	v_pk_mul_f32 v[122:123], v[172:173], v[122:123]
	s_nop 0
	v_cvt_pk_bf16_f32 v244, v122, v123
	v_lshlrev_b32_e32 v170, 16, v53
	v_and_b32_e32 v171, 0xffff0000, v53
	v_mul_f32_e32 v245, 0xbfb8aa3b, v170
	v_exp_f32_e32 v245, v245
	s_nop 0
	v_add_f32_e32 v245, 1.0, v245
	v_rcp_f32_e32 v172, v245
	v_mul_f32_e32 v245, 0xbfb8aa3b, v171
	v_exp_f32_e32 v245, v245
	s_nop 0
	v_add_f32_e32 v245, 1.0, v245
	v_rcp_f32_e32 v173, v245
	s_nop 1
	v_pk_mul_f32 v[172:173], v[172:173], v[170:171]
	s_nop 0
	v_pk_mul_f32 v[124:125], v[172:173], v[124:125]
	s_nop 0
	v_cvt_pk_bf16_f32 v245, v124, v125
	s_nop 0
	global_load_dwordx4 v[122:125], v[130:131], off offset:832
	s_waitcnt lgkmcnt(0)
	ds_read_b128 v[174:177], v103 offset:33792
	ds_read_b128 v[178:181], v103 offset:33856
	ds_read_b128 v[182:185], v103 offset:33920
	ds_read_b128 v[186:189], v103 offset:33984
	ds_read_b128 v[190:193], v103 offset:34048
	ds_read_b128 v[194:197], v103 offset:34112
	ds_read_b128 v[198:201], v103 offset:34176
	ds_read_b128 v[202:205], v103 offset:34240
	v_mfma_f32_16x16x32_bf16 v[162:165], v[206:209], v[0:3], 0
	v_mfma_f32_16x16x32_bf16 v[162:165], v[210:213], v[4:7], v[162:165]
	v_mfma_f32_16x16x32_bf16 v[162:165], v[214:217], v[8:11], v[162:165]
	v_mfma_f32_16x16x32_bf16 v[162:165], v[218:221], v[12:15], v[162:165]
	v_mfma_f32_16x16x32_bf16 v[162:165], v[222:225], v[16:19], v[162:165]
	v_mfma_f32_16x16x32_bf16 v[162:165], v[226:229], v[20:23], v[162:165]
	v_mfma_f32_16x16x32_bf16 v[162:165], v[230:233], v[24:27], v[162:165]
	v_mfma_f32_16x16x32_bf16 v[162:165], v[234:237], v[28:31], v[162:165]
	s_waitcnt vmcnt(23)
	v_lshlrev_b32_e32 v170, 16, v54
	v_and_b32_e32 v171, 0xffff0000, v54
	v_mul_f32_e32 v246, 0xbfb8aa3b, v170
	v_exp_f32_e32 v246, v246
	s_nop 0
	v_add_f32_e32 v246, 1.0, v246
	v_rcp_f32_e32 v172, v246
	v_mul_f32_e32 v246, 0xbfb8aa3b, v171
	v_exp_f32_e32 v246, v246
	s_nop 0
	v_add_f32_e32 v246, 1.0, v246
	v_rcp_f32_e32 v173, v246
	s_waitcnt vmcnt(3)
	v_pk_mul_f32 v[126:127], v[126:127], v[162:163]
	v_pk_mul_f32 v[128:129], v[128:129], v[164:165]
	v_pk_mul_f32 v[172:173], v[172:173], v[170:171]
	s_nop 0
	v_pk_mul_f32 v[126:127], v[172:173], v[126:127]
	s_nop 0
	v_cvt_pk_bf16_f32 v246, v126, v127
	v_lshlrev_b32_e32 v170, 16, v55
	v_and_b32_e32 v171, 0xffff0000, v55
	v_mul_f32_e32 v247, 0xbfb8aa3b, v170
	v_exp_f32_e32 v247, v247
	s_nop 0
	v_add_f32_e32 v247, 1.0, v247
	v_rcp_f32_e32 v172, v247
	v_mul_f32_e32 v247, 0xbfb8aa3b, v171
	v_exp_f32_e32 v247, v247
	s_nop 0
	v_add_f32_e32 v247, 1.0, v247
	v_rcp_f32_e32 v173, v247
	s_nop 1
	v_pk_mul_f32 v[172:173], v[172:173], v[170:171]
	s_nop 0
	v_pk_mul_f32 v[128:129], v[172:173], v[128:129]
	s_nop 0
	v_cvt_pk_bf16_f32 v247, v128, v129
	s_nop 0
	s_nop 1
	v_permlane32_swap_b32_e32 v244, v246
	v_permlane32_swap_b32_e32 v245, v247
	s_nop 0
	v_permlane16_swap_b32_e32 v244, v246
	v_permlane16_swap_b32_e32 v245, v247
	s_nop 0
	global_store_dwordx4 v[250:251], v[244:247], off offset:2368
	global_load_dwordx4 v[126:129], v[130:131], off offset:896
	s_waitcnt lgkmcnt(0)
	ds_read_b128 v[206:209], v103 offset:42240
	ds_read_b128 v[210:213], v103 offset:42304
	ds_read_b128 v[214:217], v103 offset:42368
	ds_read_b128 v[218:221], v103 offset:42432
	ds_read_b128 v[222:225], v103 offset:42496
	ds_read_b128 v[226:229], v103 offset:42560
	ds_read_b128 v[230:233], v103 offset:42624
	ds_read_b128 v[234:237], v103 offset:42688
	v_mfma_f32_16x16x32_bf16 v[162:165], v[174:177], v[0:3], 0
	v_mfma_f32_16x16x32_bf16 v[162:165], v[178:181], v[4:7], v[162:165]
	v_mfma_f32_16x16x32_bf16 v[162:165], v[182:185], v[8:11], v[162:165]
	v_mfma_f32_16x16x32_bf16 v[162:165], v[186:189], v[12:15], v[162:165]
	v_mfma_f32_16x16x32_bf16 v[162:165], v[190:193], v[16:19], v[162:165]
	v_mfma_f32_16x16x32_bf16 v[162:165], v[194:197], v[20:23], v[162:165]
	v_mfma_f32_16x16x32_bf16 v[162:165], v[198:201], v[24:27], v[162:165]
	v_mfma_f32_16x16x32_bf16 v[162:165], v[202:205], v[28:31], v[162:165]
	s_waitcnt vmcnt(24)
	v_lshlrev_b32_e32 v170, 16, v56
	v_and_b32_e32 v171, 0xffff0000, v56
	v_mul_f32_e32 v244, 0xbfb8aa3b, v170
	v_exp_f32_e32 v244, v244
	s_nop 0
	v_add_f32_e32 v244, 1.0, v244
	v_rcp_f32_e32 v172, v244
	v_mul_f32_e32 v244, 0xbfb8aa3b, v171
	v_exp_f32_e32 v244, v244
	s_nop 0
	v_add_f32_e32 v244, 1.0, v244
	v_rcp_f32_e32 v173, v244
	s_waitcnt vmcnt(3)
	v_pk_mul_f32 v[118:119], v[118:119], v[162:163]
	v_pk_mul_f32 v[120:121], v[120:121], v[164:165]
	v_pk_mul_f32 v[172:173], v[172:173], v[170:171]
	s_nop 0
	v_pk_mul_f32 v[118:119], v[172:173], v[118:119]
	s_nop 0
	v_cvt_pk_bf16_f32 v244, v118, v119
	v_lshlrev_b32_e32 v170, 16, v57
	v_and_b32_e32 v171, 0xffff0000, v57
	v_mul_f32_e32 v245, 0xbfb8aa3b, v170
	v_exp_f32_e32 v245, v245
	s_nop 0
	v_add_f32_e32 v245, 1.0, v245
	v_rcp_f32_e32 v172, v245
	v_mul_f32_e32 v245, 0xbfb8aa3b, v171
	v_exp_f32_e32 v245, v245
	s_nop 0
	v_add_f32_e32 v245, 1.0, v245
	v_rcp_f32_e32 v173, v245
	s_nop 1
	v_pk_mul_f32 v[172:173], v[172:173], v[170:171]
	s_nop 0
	v_pk_mul_f32 v[120:121], v[172:173], v[120:121]
	s_nop 0
	v_cvt_pk_bf16_f32 v245, v120, v121
	s_nop 0
	global_load_dwordx4 v[118:121], v[130:131], off offset:960
	s_waitcnt lgkmcnt(0)
	ds_read_b128 v[174:177], v103 offset:50688
	ds_read_b128 v[178:181], v103 offset:50752
	ds_read_b128 v[182:185], v103 offset:50816
	ds_read_b128 v[186:189], v103 offset:50880
	ds_read_b128 v[190:193], v103 offset:50944
	ds_read_b128 v[194:197], v103 offset:51008
	ds_read_b128 v[198:201], v103 offset:51072
	ds_read_b128 v[202:205], v103 offset:51136
	v_mfma_f32_16x16x32_bf16 v[162:165], v[206:209], v[0:3], 0
	v_mfma_f32_16x16x32_bf16 v[162:165], v[210:213], v[4:7], v[162:165]
	v_mfma_f32_16x16x32_bf16 v[162:165], v[214:217], v[8:11], v[162:165]
	v_mfma_f32_16x16x32_bf16 v[162:165], v[218:221], v[12:15], v[162:165]
	v_mfma_f32_16x16x32_bf16 v[162:165], v[222:225], v[16:19], v[162:165]
	v_mfma_f32_16x16x32_bf16 v[162:165], v[226:229], v[20:23], v[162:165]
	v_mfma_f32_16x16x32_bf16 v[162:165], v[230:233], v[24:27], v[162:165]
	v_mfma_f32_16x16x32_bf16 v[162:165], v[234:237], v[28:31], v[162:165]
	s_waitcnt vmcnt(24)
	v_lshlrev_b32_e32 v170, 16, v58
	v_and_b32_e32 v171, 0xffff0000, v58
	v_mul_f32_e32 v246, 0xbfb8aa3b, v170
	v_exp_f32_e32 v246, v246
	s_nop 0
	v_add_f32_e32 v246, 1.0, v246
	v_rcp_f32_e32 v172, v246
	v_mul_f32_e32 v246, 0xbfb8aa3b, v171
	v_exp_f32_e32 v246, v246
	s_nop 0
	v_add_f32_e32 v246, 1.0, v246
	v_rcp_f32_e32 v173, v246
	s_waitcnt vmcnt(3)
	v_pk_mul_f32 v[122:123], v[122:123], v[162:163]
	v_pk_mul_f32 v[124:125], v[124:125], v[164:165]
	v_pk_mul_f32 v[172:173], v[172:173], v[170:171]
	s_nop 0
	v_pk_mul_f32 v[122:123], v[172:173], v[122:123]
	s_nop 0
	v_cvt_pk_bf16_f32 v246, v122, v123
	v_lshlrev_b32_e32 v170, 16, v59
	v_and_b32_e32 v171, 0xffff0000, v59
	v_mul_f32_e32 v247, 0xbfb8aa3b, v170
	v_exp_f32_e32 v247, v247
	s_nop 0
	v_add_f32_e32 v247, 1.0, v247
	v_rcp_f32_e32 v172, v247
	v_mul_f32_e32 v247, 0xbfb8aa3b, v171
	v_exp_f32_e32 v247, v247
	s_nop 0
	v_add_f32_e32 v247, 1.0, v247
	v_rcp_f32_e32 v173, v247
	s_nop 1
	v_pk_mul_f32 v[172:173], v[172:173], v[170:171]
	s_nop 0
	v_pk_mul_f32 v[124:125], v[172:173], v[124:125]
	s_nop 0
	v_cvt_pk_bf16_f32 v247, v124, v125
	s_nop 0
	s_nop 1
	v_permlane32_swap_b32_e32 v244, v246
	v_permlane32_swap_b32_e32 v245, v247
	s_nop 0
	v_permlane16_swap_b32_e32 v244, v246
	v_permlane16_swap_b32_e32 v245, v247
	s_nop 0
	global_store_dwordx4 v[250:251], v[244:247], off offset:2432
	s_waitcnt lgkmcnt(0)
	ds_read_b128 v[206:209], v103 offset:59136
	ds_read_b128 v[210:213], v103 offset:59200
	ds_read_b128 v[214:217], v103 offset:59264
	ds_read_b128 v[218:221], v103 offset:59328
	ds_read_b128 v[222:225], v103 offset:59392
	ds_read_b128 v[226:229], v103 offset:59456
	ds_read_b128 v[230:233], v103 offset:59520
	ds_read_b128 v[234:237], v103 offset:59584
	v_mfma_f32_16x16x32_bf16 v[162:165], v[174:177], v[0:3], 0
	v_mfma_f32_16x16x32_bf16 v[162:165], v[178:181], v[4:7], v[162:165]
	v_mfma_f32_16x16x32_bf16 v[162:165], v[182:185], v[8:11], v[162:165]
	v_mfma_f32_16x16x32_bf16 v[162:165], v[186:189], v[12:15], v[162:165]
	v_mfma_f32_16x16x32_bf16 v[162:165], v[190:193], v[16:19], v[162:165]
	v_mfma_f32_16x16x32_bf16 v[162:165], v[194:197], v[20:23], v[162:165]
	v_mfma_f32_16x16x32_bf16 v[162:165], v[198:201], v[24:27], v[162:165]
	v_mfma_f32_16x16x32_bf16 v[162:165], v[202:205], v[28:31], v[162:165]
	s_waitcnt vmcnt(24)
	v_lshlrev_b32_e32 v170, 16, v60
	v_and_b32_e32 v171, 0xffff0000, v60
	v_mul_f32_e32 v244, 0xbfb8aa3b, v170
	v_exp_f32_e32 v244, v244
	s_nop 0
	v_add_f32_e32 v244, 1.0, v244
	v_rcp_f32_e32 v172, v244
	v_mul_f32_e32 v244, 0xbfb8aa3b, v171
	v_exp_f32_e32 v244, v244
	s_nop 0
	v_add_f32_e32 v244, 1.0, v244
	v_rcp_f32_e32 v173, v244
	s_waitcnt vmcnt(2)
	v_pk_mul_f32 v[126:127], v[126:127], v[162:163]
	v_pk_mul_f32 v[128:129], v[128:129], v[164:165]
	v_pk_mul_f32 v[172:173], v[172:173], v[170:171]
	s_nop 0
	v_pk_mul_f32 v[126:127], v[172:173], v[126:127]
	s_nop 0
	v_cvt_pk_bf16_f32 v244, v126, v127
	v_lshlrev_b32_e32 v170, 16, v61
	v_and_b32_e32 v171, 0xffff0000, v61
	v_mul_f32_e32 v245, 0xbfb8aa3b, v170
	v_exp_f32_e32 v245, v245
	s_nop 0
	v_add_f32_e32 v245, 1.0, v245
	v_rcp_f32_e32 v172, v245
	v_mul_f32_e32 v245, 0xbfb8aa3b, v171
	v_exp_f32_e32 v245, v245
	s_nop 0
	v_add_f32_e32 v245, 1.0, v245
	v_rcp_f32_e32 v173, v245
	s_nop 1
	v_pk_mul_f32 v[172:173], v[172:173], v[170:171]
	s_nop 0
	v_pk_mul_f32 v[128:129], v[172:173], v[128:129]
	s_nop 0
	v_cvt_pk_bf16_f32 v245, v128, v129
	s_nop 0
	s_waitcnt lgkmcnt(0)
	v_mfma_f32_16x16x32_bf16 v[162:165], v[206:209], v[0:3], 0
	v_mfma_f32_16x16x32_bf16 v[162:165], v[210:213], v[4:7], v[162:165]
	v_mfma_f32_16x16x32_bf16 v[162:165], v[214:217], v[8:11], v[162:165]
	v_mfma_f32_16x16x32_bf16 v[162:165], v[218:221], v[12:15], v[162:165]
	v_mfma_f32_16x16x32_bf16 v[162:165], v[222:225], v[16:19], v[162:165]
	v_mfma_f32_16x16x32_bf16 v[162:165], v[226:229], v[20:23], v[162:165]
	v_mfma_f32_16x16x32_bf16 v[162:165], v[230:233], v[24:27], v[162:165]
	v_mfma_f32_16x16x32_bf16 v[162:165], v[234:237], v[28:31], v[162:165]
	s_waitcnt vmcnt(23)
	v_lshlrev_b32_e32 v170, 16, v62
	v_and_b32_e32 v171, 0xffff0000, v62
	v_mul_f32_e32 v246, 0xbfb8aa3b, v170
	v_exp_f32_e32 v246, v246
	s_nop 0
	v_add_f32_e32 v246, 1.0, v246
	v_rcp_f32_e32 v172, v246
	v_mul_f32_e32 v246, 0xbfb8aa3b, v171
	v_exp_f32_e32 v246, v246
	s_nop 0
	v_add_f32_e32 v246, 1.0, v246
	v_rcp_f32_e32 v173, v246
	s_waitcnt vmcnt(1)
	v_pk_mul_f32 v[118:119], v[118:119], v[162:163]
	v_pk_mul_f32 v[120:121], v[120:121], v[164:165]
	v_pk_mul_f32 v[172:173], v[172:173], v[170:171]
	s_nop 0
	v_pk_mul_f32 v[118:119], v[172:173], v[118:119]
	s_nop 0
	v_cvt_pk_bf16_f32 v246, v118, v119
	v_lshlrev_b32_e32 v170, 16, v63
	v_and_b32_e32 v171, 0xffff0000, v63
	v_mul_f32_e32 v247, 0xbfb8aa3b, v170
	v_exp_f32_e32 v247, v247
	s_nop 0
	v_add_f32_e32 v247, 1.0, v247
	v_rcp_f32_e32 v172, v247
	v_mul_f32_e32 v247, 0xbfb8aa3b, v171
	v_exp_f32_e32 v247, v247
	s_nop 0
	v_add_f32_e32 v247, 1.0, v247
	v_rcp_f32_e32 v173, v247
	s_nop 1
	v_pk_mul_f32 v[172:173], v[172:173], v[170:171]
	s_nop 0
	v_pk_mul_f32 v[120:121], v[172:173], v[120:121]
	s_nop 0
	v_cvt_pk_bf16_f32 v247, v120, v121
	s_nop 0
	s_nop 1
	v_permlane32_swap_b32_e32 v244, v246
	v_permlane32_swap_b32_e32 v245, v247
	s_nop 0
	v_permlane16_swap_b32_e32 v244, v246
	v_permlane16_swap_b32_e32 v245, v247
	s_nop 0
	global_store_dwordx4 v[250:251], v[244:247], off offset:2496
	s_cmp_lg_u32 s0, 0
	s_cbranch_scc1 .LBB0_554
	v_mov_b32_e32 v252, 0x3000
	s_mov_b32 s13, 0
